# attention chunk loop: wait before the norm/MFMA part no longer covers the next chunk's four prefetch loads (vmcnt(4) instead of vmcnt(0)); on top of P3 mid-hook prefetch
# speedup vs baseline: 1.0001x; 1.0001x over previous
; #define GAS __attribute__((address_space(1)))
; __device__ __forceinline__ unsigned pk2(float lo, float hi) { return f2bf(lo) | (f2bf(hi) << 16); }
; __device__ __forceinline__ void unpack8(const v4u w, float (&f)[8]) { f[0] = bflo(w.x); f[1] = bfhi(w.x); f[2] = bflo(w.y); f[3] = bfhi(w.y); f[4] = bflo(w.z); f[5] = bfhi(w.z); f[6] = bflo(w.w); f[7] = bfhi(w.w); }
; __device__ __forceinline__ void attn_conv_unit(LAS unsigned char* lds, int unit, const bf16* Z, bf16* Y, float* RA,
;                                                const float* qg, const float* kg, const float* sinks, const float* convw) {
;     ...
;                 float ss = 0.f;
; #pragma unroll
;                 for (int ks = 0; ks < 4; ++ks) { float f[8]; unpack8(qw[ks], f);
; #pragma unroll
;                     for (int e = 0; e < 8; ++e) ss += f[e] * f[e]; }
;                 ss += __shfl_xor(ss, 32);
;                 const float r = (1.0f / sqrtf(ss * (1.0f / 64.0f) + EPS)) * (0.125f * LOG2E);
; #pragma unroll
;                 for (int ks = 0; ks < 4; ++ks) { float f[8]; unpack8(qw[ks], f);
;                     const f32x4 g0 = *(const f32x4*)(qg + ks * 16 + hi * 8), g1 = *(const f32x4*)(qg + ks * 16 + hi * 8 + 4);
;                     v4u o; o.x = pk2(f[0] * r * g0[0], f[1] * r * g0[1]); o.y = pk2(f[2] * r * g0[2], f[3] * r * g0[3]); o.z = pk2(f[4] * r * g1[0], f[5] * r * g1[1]); o.w = pk2(f[6] * r * g1[2], f[7] * r * g1[3]);
;                     qf[ks] = __builtin_bit_cast(bf16x8, o); }
;             }
;             if (j < 3) {
; #pragma unroll
;                 for (int ks = 0; ks < 4; ++ks) qw[ks] = __builtin_nontemporal_load((const GAS v4u*)(Z + (tokq + 32) * ZLD + h * 64 + ks * 16 + hi * 8));
.LBB0_439:
	global_load_dwordx4 v[24:27], v[132:133], off offset:16
	global_load_dwordx4 v[28:31], v[132:133], off
	global_load_dwordx4 v[16:19], v[132:133], off offset:80
	global_load_dwordx4 v[20:23], v[132:133], off offset:64
	global_load_dwordx4 v[8:11], v[132:133], off offset:144
	global_load_dwordx4 v[12:15], v[132:133], off offset:128
	global_load_dwordx4 v[0:3], v[132:133], off offset:208
	global_load_dwordx4 v[4:7], v[132:133], off offset:192
	s_waitcnt vmcnt(11)
	v_lshlrev_b32_e32 v49, 16, v81
	v_lshlrev_b32_e32 v48, 16, v80
	v_and_b32_e32 v51, 0xffff0000, v81
	v_and_b32_e32 v50, 0xffff0000, v80
	v_pk_mul_f32 v[182:183], v[48:49], v[48:49]
	v_pk_mul_f32 v[184:185], v[50:51], v[50:51]
	v_lshlrev_b32_e32 v63, 16, v83
	v_add_f32_e32 v35, v182, v184
	v_lshlrev_b32_e32 v62, 16, v82
	v_add_f32_e32 v35, v183, v35
	v_and_b32_e32 v61, 0xffff0000, v83
	v_and_b32_e32 v60, 0xffff0000, v82
	v_pk_mul_f32 v[186:187], v[62:63], v[62:63]
	v_add_f32_e32 v35, v185, v35
	v_pk_mul_f32 v[188:189], v[60:61], v[60:61]
	v_add_f32_e32 v35, v186, v35
	v_add_f32_e32 v35, v188, v35
	s_waitcnt vmcnt(10)
	v_lshlrev_b32_e32 v53, 16, v85
	v_lshlrev_b32_e32 v52, 16, v84
	v_add_f32_e32 v35, v187, v35
	v_and_b32_e32 v55, 0xffff0000, v85
	v_and_b32_e32 v54, 0xffff0000, v84
	v_pk_mul_f32 v[96:97], v[52:53], v[52:53]
	v_add_f32_e32 v35, v189, v35
	v_pk_mul_f32 v[98:99], v[54:55], v[54:55]
	v_add_f32_e32 v35, v96, v35
	v_add_f32_e32 v35, v98, v35
	v_lshlrev_b32_e32 v59, 16, v87
	v_lshlrev_b32_e32 v58, 16, v86
	v_add_f32_e32 v35, v97, v35
	s_waitcnt vmcnt(8)
	v_lshlrev_b32_e32 v38, 16, v94
	v_and_b32_e32 v36, 0xffff0000, v94
	v_and_b32_e32 v57, 0xffff0000, v87
	v_and_b32_e32 v56, 0xffff0000, v86
	v_pk_mul_f32 v[100:101], v[58:59], v[58:59]
	v_add_f32_e32 v35, v99, v35
	v_lshlrev_b32_e32 v39, 16, v95
	v_and_b32_e32 v37, 0xffff0000, v95
	v_mov_b32_e32 v40, v36
	v_mov_b32_e32 v41, v38
	v_pk_mul_f32 v[102:103], v[56:57], v[56:57]
	v_add_f32_e32 v35, v100, v35
	v_pk_mul_f32 v[68:69], v[40:41], v[40:41]
	v_mov_b32_e32 v40, v37
	v_mov_b32_e32 v41, v39
	v_add_f32_e32 v35, v102, v35
	v_pk_mul_f32 v[70:71], v[40:41], v[40:41]
	v_lshlrev_b32_e32 v41, 16, v89
	v_lshlrev_b32_e32 v40, 16, v88
	v_add_f32_e32 v35, v101, v35
	v_and_b32_e32 v43, 0xffff0000, v89
	v_and_b32_e32 v42, 0xffff0000, v88
	v_pk_mul_f32 v[72:73], v[40:41], v[40:41]
	v_add_f32_e32 v35, v103, v35
	v_pk_mul_f32 v[74:75], v[42:43], v[42:43]
	v_add_f32_e32 v35, v72, v35
	v_add_f32_e32 v35, v74, v35
	v_lshlrev_b32_e32 v47, 16, v91
	v_lshlrev_b32_e32 v46, 16, v90
	v_add_f32_e32 v35, v73, v35
	v_and_b32_e32 v45, 0xffff0000, v91
	v_and_b32_e32 v44, 0xffff0000, v90
	v_pk_mul_f32 v[76:77], v[46:47], v[46:47]
	v_add_f32_e32 v35, v75, v35
	v_pk_mul_f32 v[78:79], v[44:45], v[44:45]
	v_add_f32_e32 v35, v76, v35
	v_add_f32_e32 v35, v78, v35
	v_add_f32_e32 v35, v77, v35
	v_lshlrev_b32_e32 v34, 16, v92
	v_and_b32_e32 v33, 0xffff0000, v93
	v_add_f32_e32 v35, v79, v35
	v_lshlrev_b32_e32 v65, 16, v93
	v_and_b32_e32 v32, 0xffff0000, v92
	v_mov_b32_e32 v64, v33
	v_fmac_f32_e32 v35, v34, v34
	v_pk_mul_f32 v[66:67], v[64:65], v[64:65]
	v_fmac_f32_e32 v35, v32, v32
	v_add_f32_e32 v35, v67, v35
	v_add_f32_e32 v35, v66, v35
	v_add_f32_e32 v35, v69, v35
	v_add_f32_e32 v35, v68, v35
	v_add_f32_e32 v35, v71, v35
	v_add_f32_e32 v64, v70, v35
	ds_bpermute_b32 v66, v165, v64
	s_cmpk_eq_i32 s3, 0xc0
	s_cbranch_scc1 .LBB0_441
	global_load_dwordx4 v[80:83], v[158:159], off offset:-64 nt
	global_load_dwordx4 v[84:87], v[158:159], off offset:-32 nt
	global_load_dwordx4 v[88:91], v[158:159], off nt
	global_load_dwordx4 v[92:95], v[158:159], off offset:32 nt
	s_waitcnt vmcnt(4)
	s_branch .Lp2_att_w

; #define GAS __attribute__((address_space(1)))
; #define LAS __attribute__((address_space(3)))
; __device__ __forceinline__ unsigned pk2(float lo, float hi) { return f2bf(lo) | (f2bf(hi) << 16); }
; __device__ __forceinline__ void unpack8(const v4u w, float (&f)[8]) { f[0] = bflo(w.x); f[1] = bfhi(w.x); f[2] = bflo(w.y); f[3] = bfhi(w.y); f[4] = bflo(w.z); f[5] = bfhi(w.z); f[6] = bflo(w.w); f[7] = bfhi(w.w); }
; __device__ __forceinline__ void attn_conv_unit(LAS unsigned char* lds, int unit, const bf16* Z, bf16* Y, float* RA,
;                                                const float* qg, const float* kg, const float* sinks, const float* convw) {
;     ...
;                 float ss = 0.f;
; #pragma unroll
;                 for (int ks = 0; ks < 4; ++ks) { float f[8]; unpack8(qw[ks], f);
; #pragma unroll
;                     for (int e = 0; e < 8; ++e) ss += f[e] * f[e]; }
;                 ss += __shfl_xor(ss, 32);
;                 const float r = (1.0f / sqrtf(ss * (1.0f / 64.0f) + EPS)) * (0.125f * LOG2E);
; #pragma unroll
;                 for (int ks = 0; ks < 4; ++ks) { float f[8]; unpack8(qw[ks], f);
;                     const f32x4 g0 = *(const f32x4*)(qg + ks * 16 + hi * 8), g1 = *(const f32x4*)(qg + ks * 16 + hi * 8 + 4);
;                     v4u o; o.x = pk2(f[0] * r * g0[0], f[1] * r * g0[1]); o.y = pk2(f[2] * r * g0[2], f[3] * r * g0[3]); o.z = pk2(f[4] * r * g1[0], f[5] * r * g1[1]); o.w = pk2(f[6] * r * g1[2], f[7] * r * g1[3]);
;                     qf[ks] = __builtin_bit_cast(bf16x8, o); }
;             }
;             if (j < 3) {
; #pragma unroll
;                 for (int ks = 0; ks < 4; ++ks) qw[ks] = __builtin_nontemporal_load((const GAS v4u*)(Z + (tokq + 32) * ZLD + h * 64 + ks * 16 + hi * 8));
;             }
;             f32x16 s[5];
; #pragma unroll
;             for (int a = 0; a < 5; ++a) {
;                 f32x16 acc = {};
; #pragma unroll
;                 for (int ks = 0; ks < 4; ++ks) {
;                     const bf16x8 kf = *(const LAS bf16x8*)(ksb + (32 * (j + a)) * KS_STRIDE + ks * 32);
;                     acc = __builtin_amdgcn_mfma_f32_32x32x16_bf16(kf, qf[ks], acc, 0, 0, 0);
;                 }
;                 s[a] = acc;
;             }
.Lp2_att_w:
	v_mov_b32_e32 v68, v4
	v_mov_b32_e32 v4, v12
	s_waitcnt lgkmcnt(0)
	v_add_f32_e32 v12, v64, v66
	v_fmamk_f32 v12, v12, 0x3c800000, v169
	v_mov_b32_e32 v69, v6
	v_mov_b32_e32 v6, v5
	v_mov_b32_e32 v5, v14
	v_mov_b32_e32 v14, v13
	v_mul_f32_e32 v13, 0x4f800000, v12
	v_cmp_gt_f32_e32 vcc, s97, v12
	v_mov_b32_e32 v35, v65
	s_nop 0
	v_cndmask_b32_e32 v64, v12, v13, vcc
	v_sqrt_f32_e32 v65, v64
	v_mov_b32_e32 v12, v20
	v_mov_b32_e32 v13, v22
	v_mov_b32_e32 v22, v21
	v_add_u32_e32 v20, -1, v65
	v_fma_f32 v21, -v20, v65, v64
	v_cmp_ge_f32_e64 s[48:49], 0, v21
	v_add_u32_e32 v21, 1, v65
	s_nop 0
	v_cndmask_b32_e64 v20, v65, v20, s[48:49]
	v_fma_f32 v65, -v21, v65, v64
	v_cmp_lt_f32_e64 s[48:49], 0, v65
	s_nop 1
	v_cndmask_b32_e64 v20, v20, v21, s[48:49]
	v_mul_f32_e32 v21, 0x37800000, v20
	v_cndmask_b32_e32 v20, v20, v21, vcc
	v_cmp_class_f32_e32 vcc, v64, v170
	v_mov_b32_e32 v21, v30
	v_mov_b32_e32 v30, v29
	v_cndmask_b32_e32 v64, v20, v64, vcc
	v_div_scale_f32 v65, s[48:49], v64, v64, 1.0
	v_rcp_f32_e32 v66, v65
	v_mov_b32_e32 v20, v28
	v_fma_f32 v28, -v65, v66, 1.0
	v_fmac_f32_e32 v66, v28, v66
	v_div_scale_f32 v28, vcc, 1.0, v64, 1.0
	v_mul_f32_e32 v29, v28, v66
	v_fma_f32 v67, -v65, v29, v28
	v_fmac_f32_e32 v29, v67, v66
	v_fma_f32 v28, -v65, v29, v28
	v_div_fmas_f32 v28, v28, v66, v29
	v_div_fixup_f32 v28, v28, v64, 1.0
	v_mul_f32_e32 v28, 0x3e38aa3b, v28
	v_pk_mul_f32 v[48:49], v[28:29], v[48:49] op_sel_hi:[0,1]
	v_pk_mul_f32 v[20:21], v[20:21], v[48:49]
	v_pk_mul_f32 v[48:49], v[28:29], v[50:51] op_sel_hi:[0,1]
	v_pk_mul_f32 v[30:31], v[30:31], v[48:49]
	v_pk_mul_f32 v[48:49], v[28:29], v[62:63] op_sel_hi:[0,1]
	v_mov_b32_e32 v50, v24
	v_mov_b32_e32 v51, v26
	v_pk_mul_f32 v[48:49], v[50:51], v[48:49]
	v_pk_mul_f32 v[50:51], v[28:29], v[60:61] op_sel_hi:[0,1]
	v_mov_b32_e32 v26, v25
	v_pk_mul_f32 v[24:25], v[26:27], v[50:51]
	v_bfe_u32 v50, v30, 16, 1
	v_bfe_u32 v27, v24, 16, 1
	v_add3_u32 v24, v24, v27, s98
	v_cvt_pk_bf16_f32 v51, v49, v25
	v_bfe_u32 v26, v20, 16, 1
	v_bfe_u32 v27, v21, 16, 1
	v_bfe_u32 v29, v31, 16, 1
	v_add3_u32 v30, v30, v50, s98
	v_add3_u32 v21, v21, v27, s98
	v_add3_u32 v20, v20, v26, s98
	v_add3_u32 v29, v31, v29, s98
	v_bfe_u32 v31, v48, 16, 1
	v_lshrrev_b32_e32 v20, 16, v20
	v_lshrrev_b32_e32 v21, 16, v21
	v_add3_u32 v31, v48, v31, s98
	v_and_or_b32 v49, v29, s96, v21
	v_and_or_b32 v48, v30, s96, v20
	v_pk_mul_f32 v[20:21], v[28:29], v[52:53] op_sel_hi:[0,1]
	v_lshrrev_b32_e32 v26, 16, v31
	v_pk_mul_f32 v[12:13], v[12:13], v[20:21]
	v_pk_mul_f32 v[20:21], v[28:29], v[54:55] op_sel_hi:[0,1]
	v_and_or_b32 v50, v24, s96, v26
	v_pk_mul_f32 v[20:21], v[22:23], v[20:21]
	v_pk_mul_f32 v[22:23], v[28:29], v[58:59] op_sel_hi:[0,1]
	v_mov_b32_e32 v24, v16
	v_mov_b32_e32 v25, v18
	v_pk_mul_f32 v[22:23], v[24:25], v[22:23]
	v_pk_mul_f32 v[24:25], v[28:29], v[56:57] op_sel_hi:[0,1]
	v_mov_b32_e32 v18, v17
	v_pk_mul_f32 v[16:17], v[18:19], v[24:25]
	v_cvt_pk_bf16_f32 v98, v22, v16
	v_cvt_pk_bf16_f32 v99, v23, v17
	v_cvt_pk_bf16_f32 v97, v13, v21
	v_cvt_pk_bf16_f32 v96, v12, v20
	v_pk_mul_f32 v[12:13], v[28:29], v[40:41] op_sel_hi:[0,1]
	v_pk_mul_f32 v[4:5], v[4:5], v[12:13]
	v_pk_mul_f32 v[12:13], v[28:29], v[42:43] op_sel_hi:[0,1]
	v_pk_mul_f32 v[12:13], v[14:15], v[12:13]
	v_pk_mul_f32 v[14:15], v[28:29], v[46:47] op_sel_hi:[0,1]
	v_mov_b32_e32 v16, v8
	v_mov_b32_e32 v17, v10
	v_pk_mul_f32 v[14:15], v[16:17], v[14:15]
	v_pk_mul_f32 v[16:17], v[28:29], v[44:45] op_sel_hi:[0,1]
	v_mov_b32_e32 v10, v9
	v_pk_mul_f32 v[8:9], v[10:11], v[16:17]
	v_cvt_pk_bf16_f32 v102, v14, v8
	v_cvt_pk_bf16_f32 v103, v15, v9
	v_cvt_pk_bf16_f32 v100, v4, v12
	v_cvt_pk_bf16_f32 v101, v5, v13
	v_pk_mul_f32 v[4:5], v[28:29], v[34:35] op_sel_hi:[0,1]
	v_pk_mul_f32 v[8:9], v[68:69], v[4:5]
	v_pk_mul_f32 v[4:5], v[28:29], v[32:33] op_sel_hi:[0,1]
	v_pk_mul_f32 v[10:11], v[6:7], v[4:5]
	v_pk_mul_f32 v[4:5], v[28:29], v[38:39] op_sel_hi:[0,1]
	v_mov_b32_e32 v6, v0
	v_mov_b32_e32 v7, v2
	v_pk_mul_f32 v[12:13], v[6:7], v[4:5]
	ds_read_b128 v[4:7], v149
	v_pk_mul_f32 v[14:15], v[28:29], v[36:37] op_sel_hi:[0,1]
	v_mov_b32_e32 v2, v1
	v_pk_mul_f32 v[14:15], v[2:3], v[14:15]
	v_cvt_pk_bf16_f32 v182, v8, v10
	ds_read_b128 v[0:3], v149 offset:32
	s_waitcnt lgkmcnt(1)
	v_mfma_f32_32x32x16_bf16 v[64:79], v[4:7], v[48:51], 0
	ds_read_b128 v[4:7], v149 offset:64
	v_cvt_pk_bf16_f32 v185, v13, v15
	v_cvt_pk_bf16_f32 v183, v9, v11
	s_waitcnt lgkmcnt(1)
	v_mfma_f32_32x32x16_bf16 v[64:79], v[0:3], v[96:99], v[64:79]
	ds_read_b128 v[0:3], v149 offset:96
	v_cvt_pk_bf16_f32 v184, v12, v14
	s_waitcnt lgkmcnt(1)
	v_mfma_f32_32x32x16_bf16 v[64:79], v[4:7], v[100:103], v[64:79]
	s_andn2_b64 vcc, exec, s[60:61]
	s_waitcnt lgkmcnt(0)
	v_mfma_f32_32x32x16_bf16 v[64:79], v[0:3], v[182:185], v[64:79]
	ds_read_b128 v[0:3], v149 offset:4608
	ds_read_b128 v[4:7], v149 offset:4640
	s_waitcnt lgkmcnt(1)
	v_mfma_f32_32x32x16_bf16 v[32:47], v[0:3], v[48:51], 0
	s_waitcnt lgkmcnt(0)
	v_mfma_f32_32x32x16_bf16 v[32:47], v[4:7], v[96:99], v[32:47]
	ds_read_b128 v[0:3], v149 offset:4672
	ds_read_b128 v[4:7], v149 offset:4704
	s_waitcnt lgkmcnt(1)
	v_mfma_f32_32x32x16_bf16 v[32:47], v[0:3], v[100:103], v[32:47]
	s_waitcnt lgkmcnt(0)
	v_mfma_f32_32x32x16_bf16 v[32:47], v[4:7], v[182:185], v[32:47]
	ds_read_b128 v[0:3], v149 offset:9216
	ds_read_b128 v[4:7], v149 offset:9248
	s_waitcnt lgkmcnt(1)
	v_mfma_f32_32x32x16_bf16 v[16:31], v[0:3], v[48:51], 0
	s_waitcnt lgkmcnt(0)
	v_mfma_f32_32x32x16_bf16 v[16:31], v[4:7], v[96:99], v[16:31]
	ds_read_b128 v[0:3], v149 offset:9280
	ds_read_b128 v[4:7], v149 offset:9312
	s_waitcnt lgkmcnt(1)
	v_mfma_f32_32x32x16_bf16 v[16:31], v[0:3], v[100:103], v[16:31]
	ds_read_b128 v[0:3], v149 offset:13824
	ds_read_b128 v[52:55], v149 offset:13856
	s_waitcnt lgkmcnt(2)
	v_mfma_f32_32x32x16_bf16 v[16:31], v[4:7], v[182:185], v[16:31]
	s_waitcnt lgkmcnt(1)
	v_mfma_f32_32x32x16_bf16 v[0:15], v[0:3], v[48:51], 0
	s_waitcnt lgkmcnt(0)
	v_mfma_f32_32x32x16_bf16 v[0:15], v[52:55], v[96:99], v[0:15]
	ds_read_b128 v[52:55], v149 offset:13888
	ds_read_b128 v[56:59], v149 offset:13920
	s_waitcnt lgkmcnt(1)
	v_mfma_f32_32x32x16_bf16 v[0:15], v[52:55], v[100:103], v[0:15]
	ds_read_b128 v[52:55], v149 offset:18432
	ds_read_b128 v[186:189], v149 offset:18464
	s_waitcnt lgkmcnt(2)
	v_mfma_f32_32x32x16_bf16 v[0:15], v[56:59], v[182:185], v[0:15]
	s_waitcnt lgkmcnt(1)
	v_mfma_f32_32x32x16_bf16 v[48:63], v[52:55], v[48:51], 0
	s_waitcnt lgkmcnt(0)
	v_mfma_f32_32x32x16_bf16 v[48:63], v[186:189], v[96:99], v[48:63]
	ds_read_b128 v[96:99], v149 offset:18496
	ds_read_b128 v[186:189], v149 offset:18528
	s_waitcnt lgkmcnt(1)
	v_mfma_f32_32x32x16_bf16 v[48:63], v[96:99], v[100:103], v[48:63]
	s_waitcnt lgkmcnt(0)
	v_mfma_f32_32x32x16_bf16 v[48:63], v[186:189], v[182:185], v[48:63]
	s_cbranch_vccz .LBB0_443
; __device__ __forceinline__ void attn_conv_unit(LAS unsigned char* lds, int unit, const bf16* Z, bf16* Y, float* RA,
;                                                const float* qg, const float* kg, const float* sinks, const float* convw) {
;     ...
;             for (int r = 0; r < 16; ++r) { const int c = (r & 3) + 8 * (r >> 2) + 4 * hi;
;                 if (!(r32 < c)) s[0][r] = NEG;
;                 if (!(r32 >= c)) s[4][r] = NEG; }
	v_cndmask_b32_e64 v64, v180, v64, s[10:11]
	v_cndmask_b32_e64 v65, v65, v180, s[12:13]
	v_cndmask_b32_e64 v66, v180, v66, s[14:15]
	v_cndmask_b32_e64 v67, v180, v67, s[16:17]
	v_cndmask_b32_e64 v68, v180, v68, s[18:19]
	v_cndmask_b32_e64 v69, v180, v69, s[20:21]
	v_cndmask_b32_e64 v70, v180, v70, s[22:23]
	v_cndmask_b32_e64 v71, v180, v71, s[24:25]
	v_cndmask_b32_e64 v72, v180, v72, s[26:27]
	v_cndmask_b32_e64 v73, v180, v73, s[28:29]
	v_cndmask_b32_e64 v74, v180, v74, s[30:31]
	v_cndmask_b32_e64 v75, v180, v75, s[34:35]
	v_cndmask_b32_e64 v76, v180, v76, s[36:37]
	v_cndmask_b32_e64 v77, v180, v77, s[38:39]
	v_cndmask_b32_e64 v78, v180, v78, s[40:41]
	v_cndmask_b32_e64 v79, v180, v79, s[42:43]
	s_branch .LBB0_444
